# P11a: gelu/weight tail of single-chunk tokens deferred into the next token's gather latency window (on top of pipelined attention second task)
# baseline (speedup 1.0000x reference)
; DI void phase11a(const Params& P, char* smem_all) {
;     ...
;   const int j = RBLK & 7, lane = RTID & 63, wslot = (RBLK >> 3) * 8 + (RTID >> 6), nw = (RGRID >> 3) * 8;
;   const int l16 = lane & 15, rg = lane >> 4;
;   uint2* lst = (uint2*)(smem_all + (RTID >> 6) * 1024);
;   int nE0 = Eidx[(long)wslot * 128 + lane], nE1 = Eidx[(long)wslot * 128 + 64 + lane];
;   float nG0 = G[(long)wslot * 128 + lane], nG1 = G[(long)wslot * 128 + 64 + lane];
;   uint4 nx[4];
; #pragma unroll
;   for (int c = 0; c < 4; ++c) nx[c] = *reinterpret_cast<const uint4*>(xq + (long)wslot * 1024 + (c * 16 + l16) * 16);
;   float nsx = sxp[wslot];
.LBB0_1441:
	s_or_b64 exec, exec, s[0:1]
	s_add_u32 s24, s78, 0x1b200000
	s_addc_u32 s25, s79, 0
	s_and_b32 s0, s22, -8
	v_add_u32_e32 v212, s0, v172
	s_and_b32 s5, s22, 7
	s_mov_b32 s22, 0x8000
	s_and_b32 s4, s64, -8
	v_cmp_gt_i32_e64 s[2:3], s22, v212
	v_ashrrev_i32_e32 v213, 31, v212
	s_waitcnt lgkmcnt(0)
	s_barrier
	s_and_saveexec_b64 s[26:27], s[2:3]
	s_cbranch_execz .LBB0_1525
	s_add_u32 s28, s78, 0x2100000
	s_addc_u32 s29, s79, 0
	s_add_u32 s32, s78, 0x2000000
	s_addc_u32 s33, s79, 0
	s_add_u32 s30, s78, 0x1b000000
	s_addc_u32 s31, s79, 0
	s_add_u32 s34, s78, 0x1c200000
	s_addc_u32 s35, s79, 0
	s_mov_b32 s19, 0xfffc00
	s_mov_b32 s23, 0
	s_mov_b32 s41, 0
	v_lshlrev_b32_e32 v0, 2, v208
	v_and_b32_e32 v2, 15, v208
	v_lshrrev_b32_e32 v3, 4, v208
	v_lshlrev_b32_e32 v1, 4, v2
	v_and_b32_e32 v4, 0x3c00, v209
	v_lshlrev_b32_e32 v5, 3, v208
	v_add_u32_e32 v5, 0x2000, v5
	v_lshl_add_u32 v157, v2, 2, v3
	v_add_u32_e32 v166, 64, v208
	v_and_b32_e32 v158, 7, v208
	v_lshlrev_b32_e32 v158, 6, v158
	v_lshrrev_b32_e32 v159, 3, v208
	v_lshl_or_b32 v158, v159, 2, v158
	v_add_u32_e32 v159, 32, v158
	v_cmp_eq_u32_e64 s[80:81], 0, v2
	v_cmp_eq_u32_e64 s[82:83], 1, v2
	v_cmp_eq_u32_e64 s[84:85], 2, v2
	v_cmp_eq_u32_e64 s[86:87], 3, v2
	v_cmp_eq_u32_e64 s[88:89], 4, v2
	v_cmp_eq_u32_e64 s[90:91], 5, v2
	v_cmp_gt_u32_e64 s[94:95], 6, v2
	v_readfirstlane_b32 s6, v212
	s_nop 3
	s_mov_b32 s7, s6
	s_lshl_b32 s0, s7, 9
	s_add_u32 s8, s38, s0
	s_addc_u32 s9, s39, 0
	global_load_dword v10, v0, s[8:9]
	global_load_dword v11, v0, s[8:9] offset:256
	s_add_u32 s8, s42, s0
	s_addc_u32 s9, s43, 0
	global_load_dword v12, v0, s[8:9]
	global_load_dword v13, v0, s[8:9] offset:256
	s_lshl_b32 s0, s7, 10
	s_add_u32 s8, s62, s0
	s_addc_u32 s9, s63, 0
	global_load_dwordx4 v[32:35], v1, s[8:9]
	global_load_dwordx4 v[36:39], v1, s[8:9] offset:256
	global_load_dwordx4 v[40:43], v1, s[8:9] offset:512
	global_load_dwordx4 v[44:47], v1, s[8:9] offset:768
	s_lshl_b32 s0, s7, 2
	s_add_u32 s8, s30, s0
	s_addc_u32 s9, s31, 0
	s_load_dword s15, s[8:9], 0x0
	s_waitcnt vmcnt(0)

; DI float gelu_t(float x) { float u = 0.7978845608028654f * (x + 0.044715f * x * x * x); float e = __expf(2.f * u); float t = 1.f - 2.f / (1.f + e); return 0.5f * x * (1.f + t); }
; DI void phase11a(const Params& P, char* smem_all) {
;     ...
;       if (!pf) {
;         pf = true;
;         nE0 = Eidx[(long)tn * 128 + lane]; nE1 = Eidx[(long)tn * 128 + 64 + lane];
;         nG0 = G[(long)tn * 128 + lane]; nG1 = G[(long)tn * 128 + 64 + lane];
; #pragma unroll
;         for (int c = 0; c < 4; ++c) nx[c] = *reinterpret_cast<const uint4*>(xq + (long)tn * 1024 + (c * 16 + l16) * 16);
;         nsx = sxp[tn];
;       }
; #pragma unroll
;       for (int gi = 0; gi < 6; ++gi) {
;         if (gi < ng) {
;           int d = 0;
; #pragma unroll
;           for (int c = 0; c < 4; ++c) {
;             d = __builtin_amdgcn_sdot4((int)u[gi][c].x, (int)xr[c].x, d, false);
;             d = __builtin_amdgcn_sdot4((int)u[gi][c].y, (int)xr[c].y, d, false);
;             d = __builtin_amdgcn_sdot4((int)u[gi][c].z, (int)xr[c].z, d, false);
;             d = __builtin_amdgcn_sdot4((int)u[gi][c].w, (int)xr[c].w, d, false);
;           }
;           d = dpp_row_sum_i(d);
;           const float dot = (float)d * (su[gi] * sx);
;           const float w = gl[gi] * gelu_t(dot) * sv[gi];
;           const int p = pl[gi];
;           if (l16 == 0 && p >= 0) W2[(long)t * 128 + (p & 7) * 16 + (p >> 3)] = w;
.Lp11a_issued:
	v_lshrrev_b32_e32 v175, 8, v154
	v_and_b32_e32 v175, 0xfffc, v175
	global_load_dword v156, v175, s[32:33]
	global_load_dword v153, v175, s[28:29]
	s_cmp_lg_u32 s12, 0
	s_cbranch_scc1 .Lp11a_later
	v_mov_b64_e32 v[16:17], v[32:33]
	v_mov_b64_e32 v[18:19], v[34:35]
	v_mov_b64_e32 v[20:21], v[36:37]
	v_mov_b64_e32 v[22:23], v[38:39]
	v_mov_b64_e32 v[24:25], v[40:41]
	v_mov_b64_e32 v[26:27], v[42:43]
	v_mov_b64_e32 v[28:29], v[44:45]
	v_mov_b64_e32 v[30:31], v[46:47]
	s_lshl_b32 s0, s7, 9
	s_add_u32 s8, s38, s0
	s_addc_u32 s9, s39, 0
	global_load_dword v10, v0, s[8:9]
	global_load_dword v11, v0, s[8:9] offset:256
	s_add_u32 s8, s42, s0
	s_addc_u32 s9, s43, 0
	global_load_dword v12, v0, s[8:9]
	global_load_dword v13, v0, s[8:9] offset:256
	s_lshl_b32 s0, s7, 10
	s_add_u32 s8, s62, s0
	s_addc_u32 s9, s63, 0
	global_load_dwordx4 v[32:35], v1, s[8:9]
	global_load_dwordx4 v[36:39], v1, s[8:9] offset:256
	global_load_dwordx4 v[40:43], v1, s[8:9] offset:512
	global_load_dwordx4 v[44:47], v1, s[8:9] offset:768
	s_lshl_b32 s0, s7, 2
	s_add_u32 s8, s30, s0
	s_addc_u32 s9, s31, 0
	s_load_dword s15, s[8:9], 0x0
	s_cmp_eq_u32 s41, 0
	s_cbranch_scc1 .Lp11a_nodef
	v_cvt_f32_i32_e32 v182, v194
	v_mul_f32_e32 v183, s40, v198
	v_mul_f32_e32 v182, v183, v182
	v_mul_f32_e32 v183, 0x3d372713, v182
	v_mul_f32_e32 v183, v182, v183
	v_mul_f32_e32 v184, 0.5, v182
	v_fmac_f32_e32 v182, v182, v183
	v_mul_f32_e32 v182, 0x3f4c422a, v182
	v_add_f32_e32 v182, v182, v182
	v_mul_f32_e32 v182, 0x3fb8aa3b, v182
	v_exp_f32_e32 v182, v182
	v_and_b32_e32 v190, 0x7f, v196
	v_add_f32_e32 v182, 1.0, v182
	v_div_scale_f32 v185, s[0:1], v182, v182, 2.0
	v_rcp_f32_e32 v186, v185
	v_div_scale_f32 v187, vcc, 2.0, v182, 2.0
	v_fma_f32 v188, -v185, v186, 1.0
	v_fmac_f32_e32 v186, v188, v186
	v_mul_f32_e32 v188, v187, v186
	v_fma_f32 v189, -v185, v188, v187
	v_fmac_f32_e32 v188, v189, v186
	v_fma_f32 v187, -v185, v188, v187
	v_div_fmas_f32 v187, v187, v186, v188
	v_div_fixup_f32 v182, v187, v182, 2.0
	v_lshlrev_b32_e32 v191, 6, v190
	v_and_b32_e32 v191, 0x1c0, v191
	v_lshrrev_b32_e32 v190, 1, v190
	v_and_b32_e32 v190, 0x3c, v190
	v_or_b32_e32 v191, v191, v190
	v_sub_f32_e32 v182, 1.0, v182
	v_add_f32_e32 v182, 1.0, v182
	v_mul_f32_e32 v182, v184, v182
	v_mul_f32_e32 v182, v197, v182
	v_mul_f32_e32 v182, v195, v182
	v_mov_b32_e32 v192, v191
	v_mov_b32_e32 v193, v182
	s_mov_b64 s[72:73], s[48:49]
	s_mov_b64 s[74:75], s[50:51]
	s_mov_b32 s23, 1
	s_mov_b32 s41, 0
.Lp11a_nodef:
	s_cmp_eq_u32 s13, 4
	s_cbranch_scc1 .Lp11a_d4
	s_cmp_eq_u32 s13, 5
	s_cbranch_scc1 .Lp11a_d5
	s_cmp_eq_u32 s13, 3
	s_cbranch_scc1 .Lp11a_d3
	s_cmp_eq_u32 s13, 6
	s_cbranch_scc1 .Lp11a_d6
	s_cmp_eq_u32 s13, 2
	s_cbranch_scc1 .Lp11a_d2

; DI float gelu_t(float x) { float u = 0.7978845608028654f * (x + 0.044715f * x * x * x); float e = __expf(2.f * u); float t = 1.f - 2.f / (1.f + e); return 0.5f * x * (1.f + t); }
; DI void phase11a(const Params& P, char* smem_all) {
;     ...
;       for (int gi = 0; gi < 6; ++gi) {
;         if (gi < ng) {
;           int d = 0;
; #pragma unroll
;           for (int c = 0; c < 4; ++c) {
;             d = __builtin_amdgcn_sdot4((int)u[gi][c].x, (int)xr[c].x, d, false);
;             d = __builtin_amdgcn_sdot4((int)u[gi][c].y, (int)xr[c].y, d, false);
;             d = __builtin_amdgcn_sdot4((int)u[gi][c].z, (int)xr[c].z, d, false);
;             d = __builtin_amdgcn_sdot4((int)u[gi][c].w, (int)xr[c].w, d, false);
;           }
;           d = dpp_row_sum_i(d);
;           const float dot = (float)d * (su[gi] * sx);
;           const float w = gl[gi] * gelu_t(dot) * sv[gi];
;           const int p = pl[gi];
;           if (l16 == 0 && p >= 0) W2[(long)t * 128 + (p & 7) * 16 + (p >> 3)] = w;
.Lp11a_gelu:
	s_cmp_lg_u32 s12, 0
	s_cbranch_scc1 .Lp11a_gelu_now
	s_cmp_gt_u32 s11, 24
	s_cbranch_scc1 .Lp11a_gelu_now
	v_mov_b32_e32 v194, v152
	v_mov_b32_e32 v195, v153
	v_mov_b32_e32 v196, v154
	v_mov_b32_e32 v197, v155
	v_mov_b32_e32 v198, v156
	s_mov_b32 s40, s14
	s_mov_b64 s[48:49], s[16:17]
	s_mov_b64 s[50:51], s[36:37]
	s_mov_b32 s41, 1
	s_branch .Lp11a_chunk_end
.Lp11a_gelu_now:
	v_cvt_f32_i32_e32 v182, v152
	v_mul_f32_e32 v183, s14, v156
	v_mul_f32_e32 v182, v183, v182
	v_mul_f32_e32 v183, 0x3d372713, v182
	v_mul_f32_e32 v183, v182, v183
	v_mul_f32_e32 v184, 0.5, v182
	v_fmac_f32_e32 v182, v182, v183
	v_mul_f32_e32 v182, 0x3f4c422a, v182
	v_add_f32_e32 v182, v182, v182
	v_mul_f32_e32 v182, 0x3fb8aa3b, v182
	v_exp_f32_e32 v182, v182
	v_and_b32_e32 v190, 0x7f, v154
	v_add_f32_e32 v182, 1.0, v182
	v_div_scale_f32 v185, s[0:1], v182, v182, 2.0
	v_rcp_f32_e32 v186, v185
	v_div_scale_f32 v187, vcc, 2.0, v182, 2.0
	v_fma_f32 v188, -v185, v186, 1.0
	v_fmac_f32_e32 v186, v188, v186
	v_mul_f32_e32 v188, v187, v186
	v_fma_f32 v189, -v185, v188, v187
	v_fmac_f32_e32 v188, v189, v186
	v_fma_f32 v187, -v185, v188, v187
	v_div_fmas_f32 v187, v187, v186, v188
	v_div_fixup_f32 v182, v187, v182, 2.0
	v_lshlrev_b32_e32 v191, 6, v190
	v_and_b32_e32 v191, 0x1c0, v191
	v_lshrrev_b32_e32 v190, 1, v190
	v_and_b32_e32 v190, 0x3c, v190
	v_or_b32_e32 v191, v191, v190
	v_sub_f32_e32 v182, 1.0, v182
	v_add_f32_e32 v182, 1.0, v182
	v_mul_f32_e32 v182, v184, v182
	v_mul_f32_e32 v182, v155, v182
	v_mul_f32_e32 v182, v153, v182
	s_cmp_lg_u32 s12, 0
	s_cbranch_scc1 .Lp11a_store_now
	s_cmp_eq_u32 s23, 0
	s_cbranch_scc1 .Lp11a_pfree
	s_and_saveexec_b64 s[92:93], s[72:73]
	global_store_dword v192, v193, s[74:75]
	s_mov_b64 exec, s[92:93]
	s_mov_b32 s23, 0
.Lp11a_pfree:
	v_mov_b32_e32 v192, v191
	v_mov_b32_e32 v193, v182
	s_mov_b64 s[72:73], s[16:17]
	s_mov_b64 s[74:75], s[36:37]
	s_mov_b32 s23, 1
	s_branch .Lp11a_chunk_end

; DI float gelu_t(float x) { float u = 0.7978845608028654f * (x + 0.044715f * x * x * x); float e = __expf(2.f * u); float t = 1.f - 2.f / (1.f + e); return 0.5f * x * (1.f + t); }
; DI void phase11a(const Params& P, char* smem_all) {
;     ...
;           const float dot = (float)d * (su[gi] * sx);
;           const float w = gl[gi] * gelu_t(dot) * sv[gi];
;           const int p = pl[gi];
;           if (l16 == 0 && p >= 0) W2[(long)t * 128 + (p & 7) * 16 + (p >> 3)] = w;
.Lp11a_done:
	s_cmp_eq_u32 s41, 0
	s_cbranch_scc1 .Lp11a_nodef2
	v_cvt_f32_i32_e32 v182, v194
	v_mul_f32_e32 v183, s40, v198
	v_mul_f32_e32 v182, v183, v182
	v_mul_f32_e32 v183, 0x3d372713, v182
	v_mul_f32_e32 v183, v182, v183
	v_mul_f32_e32 v184, 0.5, v182
	v_fmac_f32_e32 v182, v182, v183
	v_mul_f32_e32 v182, 0x3f4c422a, v182
	v_add_f32_e32 v182, v182, v182
	v_mul_f32_e32 v182, 0x3fb8aa3b, v182
	v_exp_f32_e32 v182, v182
	v_and_b32_e32 v190, 0x7f, v196
	v_add_f32_e32 v182, 1.0, v182
	v_div_scale_f32 v185, s[0:1], v182, v182, 2.0
	v_rcp_f32_e32 v186, v185
	v_div_scale_f32 v187, vcc, 2.0, v182, 2.0
	v_fma_f32 v188, -v185, v186, 1.0
	v_fmac_f32_e32 v186, v188, v186
	v_mul_f32_e32 v188, v187, v186
	v_fma_f32 v189, -v185, v188, v187
	v_fmac_f32_e32 v188, v189, v186
	v_fma_f32 v187, -v185, v188, v187
	v_div_fmas_f32 v187, v187, v186, v188
	v_div_fixup_f32 v182, v187, v182, 2.0
	v_lshlrev_b32_e32 v191, 6, v190
	v_and_b32_e32 v191, 0x1c0, v191
	v_lshrrev_b32_e32 v190, 1, v190
	v_and_b32_e32 v190, 0x3c, v190
	v_or_b32_e32 v191, v191, v190
	v_sub_f32_e32 v182, 1.0, v182
	v_add_f32_e32 v182, 1.0, v182
	v_mul_f32_e32 v182, v184, v182
	v_mul_f32_e32 v182, v197, v182
	v_mul_f32_e32 v182, v195, v182
	s_and_saveexec_b64 s[92:93], s[48:49]
	global_store_dword v191, v182, s[50:51]
	s_mov_b64 exec, s[92:93]
	s_mov_b32 s41, 0
